# layer-1 in-proj epilogue reads its row statistics from LDS (16 KB block DMAd during the peeled first K iteration) instead of 8 global loads + vmcnt(0) per tile
# speedup vs baseline: 1.0142x; 1.0002x over previous
.LBB0_358:
	v_lshlrev_b32_e32 v13, 2, v189
	v_lshl_or_b32 v194, s3, 6, v189
	v_lshl_or_b32 v12, v189, 6, v191
	s_lshl_b32 s3, s3, 13
	v_and_b32_e32 v13, 32, v13
	s_add_i32 m0, s45, 0x18000
	v_lshl_add_u64 v[0:1], v[0:1], 0, s[36:37]
	v_bitop3_b32 v12, v12, s3, v13 bitop3:0xde
	s_lshl_b32 s3, s10, 5
	s_waitcnt vmcnt(2)
	s_barrier
	global_load_lds_dwordx4 v[0:1], off
	v_lshl_add_u64 v[0:1], v[2:3], 0, s[36:37]
	s_add_i32 m0, s45, 0x1a000
	s_add_i32 s10, s45, 0x8000
	global_load_lds_dwordx4 v[0:1], off
	v_lshl_add_u64 v[0:1], v[8:9], 0, s[36:37]
	s_mov_b32 m0, s10
	s_add_i32 s11, s45, 0xa000
	global_load_lds_dwordx4 v[0:1], off
	v_lshl_add_u64 v[0:1], v[10:11], 0, s[36:37]
	s_mov_b32 m0, s11
	s_and_b32 s3, s3, 0x60
	global_load_lds_dwordx4 v[0:1], off
	s_add_i32 m0, s45, 0x1c000
	v_lshl_add_u64 v[0:1], v[4:5], 0, s[36:37]
	global_load_lds_dwordx4 v[0:1], off
	v_lshl_add_u64 v[0:1], v[6:7], 0, s[36:37]
	s_add_i32 m0, s45, 0x1e000
	s_add_i32 s13, s31, -2
	global_load_lds_dwordx4 v[0:1], off
	s_cmpk_lt_u32 s2, 0x100
	v_lshl_or_b32 v195, s3, 7, v192
	s_cselect_b64 s[74:75], -1, 0
	v_or_b32_e32 v196, s3, v190
	s_lshl_b32 s3, s82, 3
	v_cvt_f32_u32_e32 v0, s3
	s_lshr_b32 s2, s73, 3
	s_and_b32 s85, s73, 6
	s_add_i32 s58, s2, 1
	v_rcp_iflag_f32_e32 v0, v0
	s_cmp_lg_u64 s[42:43], 0
	s_cselect_b64 s[90:91], -1, 0
	s_cselect_b32 s100, s42, s88
	s_cselect_b32 s101, s43, s89
	s_sub_i32 s14, 0, s3
	v_mul_f32_e32 v0, 0x4f7ffffe, v0
	v_cvt_u32_f32_e32 v0, v0
	s_waitcnt vmcnt(6)
	v_mov_b32_e32 v157, v155
	s_mov_b32 s84, s2
	v_readfirstlane_b32 s15, v0
	s_mul_i32 s14, s14, s15
	s_mul_hi_u32 s14, s15, s14
	v_lshl_add_u64 v[164:165], s[42:43], 0, v[156:157]
	s_mov_b32 s18, 0
	s_add_i32 s33, s15, s14
	v_lshl_add_u64 v[166:167], s[8:9], 0, v[158:159]
	v_lshl_add_u64 v[168:169], s[8:9], 0, v[160:161]
	v_add_u32_e32 v157, 0, v12
	s_movk_i32 s69, 0x2000
	s_barrier
	v_lshlrev_b32_e32 v248, 4, v199
	s_branch .LBB0_361

.Lpeel_join375_1:
	s_waitcnt lgkmcnt(0)
	s_barrier
	s_setprio 1
	s_waitcnt lgkmcnt(0)
	v_mfma_f32_16x16x32_bf16 v[120:123], v[128:131], v[178:181], 0
	v_mfma_f32_16x16x32_bf16 v[124:127], v[136:139], v[178:181], 0
	v_mfma_f32_16x16x32_bf16 v[100:103], v[128:131], v[206:209], 0
	v_mfma_f32_16x16x32_bf16 v[96:99], v[136:139], v[206:209], 0
	v_mfma_f32_16x16x32_bf16 v[84:87], v[128:131], v[214:217], 0
	v_mfma_f32_16x16x32_bf16 v[80:83], v[136:139], v[214:217], 0
	v_mfma_f32_16x16x32_bf16 v[68:71], v[128:131], v[222:225], 0
	v_mfma_f32_16x16x32_bf16 v[64:67], v[136:139], v[222:225], 0
	v_mfma_f32_16x16x32_bf16 v[120:123], v[132:135], v[202:205], v[120:123]
	v_mfma_f32_16x16x32_bf16 v[124:127], v[140:143], v[202:205], v[124:127]
	v_mfma_f32_16x16x32_bf16 v[100:103], v[132:135], v[210:213], v[100:103]
	v_mfma_f32_16x16x32_bf16 v[96:99], v[140:143], v[210:213], v[96:99]
	v_mfma_f32_16x16x32_bf16 v[84:87], v[132:135], v[218:221], v[84:87]
	v_mfma_f32_16x16x32_bf16 v[80:83], v[140:143], v[218:221], v[80:83]
	v_mfma_f32_16x16x32_bf16 v[68:71], v[132:135], v[226:229], v[68:71]
	v_mfma_f32_16x16x32_bf16 v[64:67], v[140:143], v[226:229], v[64:67]
	s_setprio 0
	s_setprio 1
	v_mfma_f32_16x16x32_bf16 v[116:119], v[144:147], v[178:181], 0
	v_mfma_f32_16x16x32_bf16 v[112:115], v[170:173], v[178:181], 0
	v_mfma_f32_16x16x32_bf16 v[108:111], v[144:147], v[206:209], 0
	v_mfma_f32_16x16x32_bf16 v[104:107], v[170:173], v[206:209], 0
	v_mfma_f32_16x16x32_bf16 v[92:95], v[144:147], v[214:217], 0
	v_mfma_f32_16x16x32_bf16 v[88:91], v[170:173], v[214:217], 0
	v_mfma_f32_16x16x32_bf16 v[76:79], v[144:147], v[222:225], 0
	v_mfma_f32_16x16x32_bf16 v[72:75], v[170:173], v[222:225], 0
	v_mfma_f32_16x16x32_bf16 v[116:119], v[148:151], v[202:205], v[116:119]
	v_mfma_f32_16x16x32_bf16 v[112:115], v[174:177], v[202:205], v[112:115]
	v_mfma_f32_16x16x32_bf16 v[108:111], v[148:151], v[210:213], v[108:111]
	v_mfma_f32_16x16x32_bf16 v[104:107], v[174:177], v[210:213], v[104:107]
	v_mfma_f32_16x16x32_bf16 v[92:95], v[148:151], v[218:221], v[92:95]
	v_mfma_f32_16x16x32_bf16 v[88:91], v[174:177], v[218:221], v[88:91]
	v_mfma_f32_16x16x32_bf16 v[76:79], v[148:151], v[226:229], v[76:79]
	v_mfma_f32_16x16x32_bf16 v[72:75], v[174:177], v[226:229], v[72:75]
	s_setprio 0
	s_barrier
	s_add_i32 s12, s12, s17
	v_lshl_add_u64 v[230:231], s[14:15], 0, v[154:155]
	s_mov_b32 m0, s12
	ds_read_b128 v[178:181], v157 offset:16384
	ds_read_b128 v[202:205], v157 offset:17408
	ds_read_b128 v[206:209], v157 offset:18432
	ds_read_b128 v[210:213], v157 offset:19456
	ds_read_b128 v[214:217], v157 offset:20480
	ds_read_b128 v[218:221], v157 offset:21504
	ds_read_b128 v[222:225], v157 offset:22528
	ds_read_b128 v[226:229], v157 offset:23552
	global_load_lds_dwordx4 v[230:231], off
	s_add_i32 m0, s12, 0x2000
	v_lshl_add_u64 v[232:233], s[14:15], 0, v[162:163]
	s_add_u32 s14, s14, s24
	s_addc_u32 s15, s15, s25
	s_add_i32 s2, s2, s17
	global_load_lds_dwordx4 v[232:233], off
	v_lshl_add_u64 v[234:235], s[14:15], 0, v[154:155]
	s_mov_b32 m0, s2
	v_lshl_add_u64 v[236:237], s[14:15], 0, v[162:163]
	global_load_lds_dwordx4 v[234:235], off
	s_add_i32 m0, s2, 0x2000
	v_lshl_add_u64 v[238:239], s[0:1], 0, v[158:159]
	global_load_lds_dwordx4 v[236:237], off
	s_mov_b32 m0, s45
	v_lshl_add_u64 v[240:241], s[0:1], 0, v[160:161]
	global_load_lds_dwordx4 v[238:239], off
	s_mov_b32 m0, s83
	s_nop 0
	global_load_lds_dwordx4 v[240:241], off
	s_lshl_b32 s99, s17, 1
	s_add_i32 m0, s99, 0x20000
	s_lshl_b32 s98, s65, 14
	s_add_i32 s98, s98, s99
	s_add_u32 s98, s100, s98
	s_addc_u32 s99, s101, 0
	global_load_lds_dwordx4 v248, s[98:99]
	global_load_lds_dwordx4 v248, s[98:99] offset:1024
	s_cmp_eq_u32 s18, 1
	s_cbranch_scc1 .Lpeel_strict375_2
	s_waitcnt vmcnt(18)
	s_branch .Lpeel_join375_2
.Lpeel_strict375_2:
	s_waitcnt vmcnt(10)
.Lpeel_join375_2:
	s_waitcnt lgkmcnt(0)
	s_barrier
	s_setprio 1
	s_waitcnt lgkmcnt(0)
	v_mfma_f32_16x16x32_bf16 v[52:55], v[128:131], v[178:181], 0
	v_mfma_f32_16x16x32_bf16 v[48:51], v[136:139], v[178:181], 0
	v_mfma_f32_16x16x32_bf16 v[36:39], v[128:131], v[206:209], 0
	v_mfma_f32_16x16x32_bf16 v[32:35], v[136:139], v[206:209], 0
	v_mfma_f32_16x16x32_bf16 v[20:23], v[128:131], v[214:217], 0
	v_mfma_f32_16x16x32_bf16 v[16:19], v[136:139], v[214:217], 0
	v_mfma_f32_16x16x32_bf16 v[4:7], v[128:131], v[222:225], 0
	v_mfma_f32_16x16x32_bf16 v[0:3], v[136:139], v[222:225], 0
	v_mfma_f32_16x16x32_bf16 v[52:55], v[132:135], v[202:205], v[52:55]
	v_mfma_f32_16x16x32_bf16 v[48:51], v[140:143], v[202:205], v[48:51]
	v_mfma_f32_16x16x32_bf16 v[36:39], v[132:135], v[210:213], v[36:39]
	v_mfma_f32_16x16x32_bf16 v[32:35], v[140:143], v[210:213], v[32:35]
	v_mfma_f32_16x16x32_bf16 v[20:23], v[132:135], v[218:221], v[20:23]
	v_mfma_f32_16x16x32_bf16 v[16:19], v[140:143], v[218:221], v[16:19]
	v_mfma_f32_16x16x32_bf16 v[4:7], v[132:135], v[226:229], v[4:7]
	v_mfma_f32_16x16x32_bf16 v[0:3], v[140:143], v[226:229], v[0:3]
	s_setprio 0
	s_setprio 1
	v_mfma_f32_16x16x32_bf16 v[60:63], v[144:147], v[178:181], 0
	v_mfma_f32_16x16x32_bf16 v[56:59], v[170:173], v[178:181], 0
	v_mfma_f32_16x16x32_bf16 v[44:47], v[144:147], v[206:209], 0
	v_mfma_f32_16x16x32_bf16 v[40:43], v[170:173], v[206:209], 0
	v_mfma_f32_16x16x32_bf16 v[28:31], v[144:147], v[214:217], 0
	v_mfma_f32_16x16x32_bf16 v[24:27], v[170:173], v[214:217], 0
	v_mfma_f32_16x16x32_bf16 v[12:15], v[144:147], v[222:225], 0
	v_mfma_f32_16x16x32_bf16 v[8:11], v[170:173], v[222:225], 0
	v_mfma_f32_16x16x32_bf16 v[60:63], v[148:151], v[202:205], v[60:63]
	v_mfma_f32_16x16x32_bf16 v[56:59], v[174:177], v[202:205], v[56:59]
	v_mfma_f32_16x16x32_bf16 v[44:47], v[148:151], v[210:213], v[44:47]
	v_mfma_f32_16x16x32_bf16 v[40:43], v[174:177], v[210:213], v[40:43]
	v_mfma_f32_16x16x32_bf16 v[28:31], v[148:151], v[218:221], v[28:31]
	v_mfma_f32_16x16x32_bf16 v[24:27], v[174:177], v[218:221], v[24:27]
	v_mfma_f32_16x16x32_bf16 v[12:15], v[148:151], v[226:229], v[12:15]
	v_mfma_f32_16x16x32_bf16 v[8:11], v[174:177], v[226:229], v[8:11]
	s_setprio 0
	s_barrier
	s_add_i32 s2, 0, 0x18000
	s_add_i32 s12, 0, 0x1c000
	v_add_u32_e32 v140, s2, v195
	v_add_u32_e32 v174, s12, v195
	ds_read_b128 v[128:131], v140
	ds_read_b128 v[132:135], v140 offset:1024
	ds_read_b128 v[136:139], v140 offset:2048
	ds_read_b128 v[140:143], v140 offset:3072
	ds_read_b128 v[144:147], v174
	ds_read_b128 v[148:151], v174 offset:1024
	ds_read_b128 v[170:173], v174 offset:2048
	ds_read_b128 v[174:177], v174 offset:3072
	s_add_u32 s0, s0, s8
	s_addc_u32 s1, s1, s9
	s_mov_b32 m0, s28
	v_lshl_add_u64 v[242:243], s[0:1], 0, v[158:159]
	ds_read_b128 v[178:181], v157 offset:32768
	ds_read_b128 v[202:205], v157 offset:33792
	ds_read_b128 v[206:209], v157 offset:34816
	ds_read_b128 v[210:213], v157 offset:35840
	ds_read_b128 v[214:217], v157 offset:36864
	ds_read_b128 v[218:221], v157 offset:37888
	ds_read_b128 v[222:225], v157 offset:38912
	ds_read_b128 v[226:229], v157 offset:39936
	global_load_lds_dwordx4 v[242:243], off
	v_lshl_add_u64 v[242:243], s[0:1], 0, v[160:161]
	s_mov_b32 m0, s29
	s_nop 0
	global_load_lds_dwordx4 v[242:243], off
	s_waitcnt vmcnt(10)
	s_waitcnt lgkmcnt(0)
	s_barrier
	s_setprio 1
	s_waitcnt lgkmcnt(0)
	v_mfma_f32_16x16x32_bf16 v[120:123], v[128:131], v[178:181], v[120:123]
	v_mfma_f32_16x16x32_bf16 v[124:127], v[136:139], v[178:181], v[124:127]
	v_mfma_f32_16x16x32_bf16 v[100:103], v[128:131], v[206:209], v[100:103]
	v_mfma_f32_16x16x32_bf16 v[96:99], v[136:139], v[206:209], v[96:99]
	v_mfma_f32_16x16x32_bf16 v[84:87], v[128:131], v[214:217], v[84:87]
	v_mfma_f32_16x16x32_bf16 v[80:83], v[136:139], v[214:217], v[80:83]
	v_mfma_f32_16x16x32_bf16 v[68:71], v[128:131], v[222:225], v[68:71]
	v_mfma_f32_16x16x32_bf16 v[64:67], v[136:139], v[222:225], v[64:67]
	v_mfma_f32_16x16x32_bf16 v[120:123], v[132:135], v[202:205], v[120:123]
	v_mfma_f32_16x16x32_bf16 v[124:127], v[140:143], v[202:205], v[124:127]
	v_mfma_f32_16x16x32_bf16 v[100:103], v[132:135], v[210:213], v[100:103]
	v_mfma_f32_16x16x32_bf16 v[96:99], v[140:143], v[210:213], v[96:99]
	v_mfma_f32_16x16x32_bf16 v[84:87], v[132:135], v[218:221], v[84:87]
	v_mfma_f32_16x16x32_bf16 v[80:83], v[140:143], v[218:221], v[80:83]
	v_mfma_f32_16x16x32_bf16 v[68:71], v[132:135], v[226:229], v[68:71]
	v_mfma_f32_16x16x32_bf16 v[64:67], v[140:143], v[226:229], v[64:67]
	s_setprio 0
	s_setprio 1
	v_mfma_f32_16x16x32_bf16 v[116:119], v[144:147], v[178:181], v[116:119]
	v_mfma_f32_16x16x32_bf16 v[112:115], v[170:173], v[178:181], v[112:115]
	v_mfma_f32_16x16x32_bf16 v[108:111], v[144:147], v[206:209], v[108:111]
	v_mfma_f32_16x16x32_bf16 v[104:107], v[170:173], v[206:209], v[104:107]
	v_mfma_f32_16x16x32_bf16 v[92:95], v[144:147], v[214:217], v[92:95]
	v_mfma_f32_16x16x32_bf16 v[88:91], v[170:173], v[214:217], v[88:91]
	v_mfma_f32_16x16x32_bf16 v[76:79], v[144:147], v[222:225], v[76:79]
	v_mfma_f32_16x16x32_bf16 v[72:75], v[170:173], v[222:225], v[72:75]
	v_mfma_f32_16x16x32_bf16 v[116:119], v[148:151], v[202:205], v[116:119]
	v_mfma_f32_16x16x32_bf16 v[112:115], v[174:177], v[202:205], v[112:115]
	v_mfma_f32_16x16x32_bf16 v[108:111], v[148:151], v[210:213], v[108:111]
	v_mfma_f32_16x16x32_bf16 v[104:107], v[174:177], v[210:213], v[104:107]
	v_mfma_f32_16x16x32_bf16 v[92:95], v[148:151], v[218:221], v[92:95]
	v_mfma_f32_16x16x32_bf16 v[88:91], v[174:177], v[218:221], v[88:91]
	v_mfma_f32_16x16x32_bf16 v[76:79], v[148:151], v[226:229], v[76:79]
	v_mfma_f32_16x16x32_bf16 v[72:75], v[174:177], v[226:229], v[72:75]
	s_setprio 0
	s_barrier
	s_add_i32 s0, s2, s17
	v_lshl_add_u64 v[230:231], v[230:231], 0, s[36:37]
	s_mov_b32 m0, s0
	ds_read_b128 v[178:181], v157 offset:49152
	ds_read_b128 v[202:205], v157 offset:50176
	ds_read_b128 v[206:209], v157 offset:51200
	ds_read_b128 v[210:213], v157 offset:52224
	ds_read_b128 v[214:217], v157 offset:53248
	ds_read_b128 v[218:221], v157 offset:54272
	ds_read_b128 v[222:225], v157 offset:55296
	ds_read_b128 v[226:229], v157 offset:56320
	global_load_lds_dwordx4 v[230:231], off
	v_lshl_add_u64 v[230:231], v[232:233], 0, s[36:37]
	s_add_i32 m0, s0, 0x2000
	s_add_i32 s0, s12, s17
	global_load_lds_dwordx4 v[230:231], off
	v_lshl_add_u64 v[230:231], v[234:235], 0, s[36:37]
	s_mov_b32 m0, s0
	s_nop 0
	global_load_lds_dwordx4 v[230:231], off
	v_lshl_add_u64 v[230:231], v[236:237], 0, s[36:37]
	s_add_i32 m0, s0, 0x2000
	s_nop 0
	global_load_lds_dwordx4 v[230:231], off
	v_lshl_add_u64 v[230:231], v[238:239], 0, s[36:37]
	s_mov_b32 m0, s10
	s_nop 0
	global_load_lds_dwordx4 v[230:231], off
	v_lshl_add_u64 v[230:231], v[240:241], 0, s[36:37]
	s_mov_b32 m0, s11
	s_nop 0
	global_load_lds_dwordx4 v[230:231], off
	s_waitcnt vmcnt(10)
	s_waitcnt lgkmcnt(0)
	s_barrier
	s_setprio 1
	s_waitcnt lgkmcnt(0)
	v_mfma_f32_16x16x32_bf16 v[52:55], v[128:131], v[178:181], v[52:55]
	v_mfma_f32_16x16x32_bf16 v[48:51], v[136:139], v[178:181], v[48:51]
	v_mfma_f32_16x16x32_bf16 v[36:39], v[128:131], v[206:209], v[36:39]
	v_mfma_f32_16x16x32_bf16 v[32:35], v[136:139], v[206:209], v[32:35]
	v_mfma_f32_16x16x32_bf16 v[20:23], v[128:131], v[214:217], v[20:23]
	v_mfma_f32_16x16x32_bf16 v[16:19], v[136:139], v[214:217], v[16:19]
	v_mfma_f32_16x16x32_bf16 v[4:7], v[128:131], v[222:225], v[4:7]
	v_mfma_f32_16x16x32_bf16 v[0:3], v[136:139], v[222:225], v[0:3]
	v_mfma_f32_16x16x32_bf16 v[52:55], v[132:135], v[202:205], v[52:55]
	v_mfma_f32_16x16x32_bf16 v[48:51], v[140:143], v[202:205], v[48:51]
	v_mfma_f32_16x16x32_bf16 v[36:39], v[132:135], v[210:213], v[36:39]
	v_mfma_f32_16x16x32_bf16 v[32:35], v[140:143], v[210:213], v[32:35]
	v_mfma_f32_16x16x32_bf16 v[20:23], v[132:135], v[218:221], v[20:23]
	v_mfma_f32_16x16x32_bf16 v[16:19], v[140:143], v[218:221], v[16:19]
	v_mfma_f32_16x16x32_bf16 v[4:7], v[132:135], v[226:229], v[4:7]
	v_mfma_f32_16x16x32_bf16 v[0:3], v[140:143], v[226:229], v[0:3]
	s_setprio 0
	s_setprio 1
	v_mfma_f32_16x16x32_bf16 v[60:63], v[144:147], v[178:181], v[60:63]
	v_mfma_f32_16x16x32_bf16 v[56:59], v[170:173], v[178:181], v[56:59]
	v_mfma_f32_16x16x32_bf16 v[44:47], v[144:147], v[206:209], v[44:47]
	v_mfma_f32_16x16x32_bf16 v[40:43], v[170:173], v[206:209], v[40:43]
	v_mfma_f32_16x16x32_bf16 v[28:31], v[144:147], v[214:217], v[28:31]
	v_mfma_f32_16x16x32_bf16 v[24:27], v[170:173], v[214:217], v[24:27]
	v_mfma_f32_16x16x32_bf16 v[12:15], v[144:147], v[222:225], v[12:15]
	v_mfma_f32_16x16x32_bf16 v[8:11], v[170:173], v[222:225], v[8:11]
	v_mfma_f32_16x16x32_bf16 v[60:63], v[148:151], v[202:205], v[60:63]
	v_mfma_f32_16x16x32_bf16 v[56:59], v[174:177], v[202:205], v[56:59]
	v_mfma_f32_16x16x32_bf16 v[44:47], v[148:151], v[210:213], v[44:47]
	v_mfma_f32_16x16x32_bf16 v[40:43], v[174:177], v[210:213], v[40:43]
	v_mfma_f32_16x16x32_bf16 v[28:31], v[148:151], v[218:221], v[28:31]
	v_mfma_f32_16x16x32_bf16 v[24:27], v[174:177], v[218:221], v[24:27]
	v_mfma_f32_16x16x32_bf16 v[12:15], v[148:151], v[226:229], v[12:15]
	v_mfma_f32_16x16x32_bf16 v[8:11], v[174:177], v[226:229], v[8:11]
	s_setprio 0
	s_barrier
	s_add_u32 s42, s42, 0x100
	s_addc_u32 s43, s43, 0
	s_add_u32 s46, s46, 0x100
	s_addc_u32 s47, s47, 0
	s_cmp_ge_u32 s97, s31
	s_mov_b32 s0, s97

.LBB0_394:
	v_lshl_add_u32 v170, s65, 8, v194
	v_ashrrev_i32_e32 v171, 31, v170
	s_andn2_b64 vcc, exec, s[90:91]
	v_or_b32_e32 v176, 16, v170
	v_or_b32_e32 v174, 32, v170
	v_or_b32_e32 v172, 48, v170
	s_cbranch_vccnz .LBB0_396
	v_and_b32_e32 v129, 48, v199
	v_lshl_add_u32 v128, v194, 6, v129
	v_add_u32_e32 v128, 0x20000, v128
	ds_read_b128 v[178:181], v128
	ds_read_b128 v[202:205], v128 offset:1024
	ds_read_b128 v[144:147], v128 offset:2048
	ds_read_b128 v[148:151], v128 offset:3072
	ds_read_b128 v[136:139], v128 offset:8192
	ds_read_b128 v[140:143], v128 offset:9216
	ds_read_b128 v[132:135], v128 offset:10240
	ds_read_b128 v[128:131], v128 offset:11264
	v_and_b32_e32 v175, 64, v199
	v_xor_b32_e32 v173, 16, v199
	v_add_u32_e32 v177, 64, v175
	v_cmp_lt_i32_e32 vcc, v173, v177
	s_mov_b32 s0, 0x358637bd
	s_mov_b32 s2, 0x3a800000
	v_cndmask_b32_e32 v173, v199, v173, vcc
	v_lshlrev_b32_e32 v175, 2, v173
	v_xor_b32_e32 v173, 32, v199
	v_cmp_lt_i32_e32 vcc, v173, v177
	s_waitcnt lgkmcnt(0)
	v_mov_b32_e32 v206, v178
	v_mov_b32_e32 v207, v202
	v_mov_b32_e32 v202, v179
	v_pk_add_f32 v[178:179], v[206:207], v[202:203]
	v_mov_b32_e32 v202, v180
	v_mov_b32_e32 v203, v204
	v_mov_b32_e32 v204, v181
	v_pk_add_f32 v[180:181], v[202:203], v[204:205]
	v_cndmask_b32_e32 v173, v199, v173, vcc
	v_pk_add_f32 v[178:179], v[178:179], v[180:181]
	ds_bpermute_b32 v180, v175, v178
	ds_bpermute_b32 v181, v175, v179
	v_lshlrev_b32_e32 v173, 2, v173
	s_waitcnt lgkmcnt(0)
	v_pk_add_f32 v[178:179], v[178:179], v[180:181]
	ds_bpermute_b32 v180, v173, v178
	ds_bpermute_b32 v181, v173, v179
	s_waitcnt lgkmcnt(0)
	v_pk_add_f32 v[178:179], v[178:179], v[180:181]
	v_mov_b64_e32 v[180:181], s[0:1]
	v_pk_fma_f32 v[178:179], v[178:179], s[2:3], v[180:181] op_sel_hi:[1,0,0]
	s_mov_b32 s0, 0x45800000
	v_mul_f32_e32 v177, 0x4b800000, v178
	v_cmp_gt_f32_e64 s[42:43], s19, v178
	v_cmp_gt_f32_e32 vcc, s19, v179
	s_nop 0
	v_cndmask_b32_e64 v177, v178, v177, s[42:43]
	v_rsq_f32_e32 v178, v177
	v_mul_f32_e32 v177, 0x4b800000, v179
	v_cndmask_b32_e32 v177, v179, v177, vcc
	v_rsq_f32_e32 v179, v177
	s_nop 0
	v_pk_mul_f32 v[202:203], v[178:179], s[0:1] op_sel_hi:[1,0]
	s_nop 0
	v_cndmask_b32_e64 v178, v178, v202, s[42:43]
	v_cndmask_b32_e32 v179, v179, v203, vcc
	v_mov_b32_e32 v202, v144
	v_mov_b32_e32 v203, v148
	v_mov_b32_e32 v148, v145
	v_pk_add_f32 v[144:145], v[202:203], v[148:149]
	v_mov_b32_e32 v148, v146
	v_mov_b32_e32 v149, v150
	v_mov_b32_e32 v150, v147
	v_pk_add_f32 v[146:147], v[148:149], v[150:151]
	s_nop 0
	v_pk_add_f32 v[144:145], v[144:145], v[146:147]
	ds_bpermute_b32 v146, v175, v144
	ds_bpermute_b32 v147, v175, v145
	s_waitcnt lgkmcnt(0)
	v_pk_add_f32 v[144:145], v[144:145], v[146:147]
	ds_bpermute_b32 v146, v173, v144
	ds_bpermute_b32 v147, v173, v145
	s_waitcnt lgkmcnt(0)
	v_pk_add_f32 v[144:145], v[144:145], v[146:147]
	s_nop 0
	v_pk_fma_f32 v[144:145], v[144:145], s[2:3], v[180:181] op_sel_hi:[1,0,0]
	s_nop 0
	v_mul_f32_e32 v146, 0x4b800000, v144
	v_cmp_gt_f32_e64 s[42:43], s19, v144
	v_cmp_gt_f32_e32 vcc, s19, v145
	s_nop 0
	v_cndmask_b32_e64 v144, v144, v146, s[42:43]
	v_mul_f32_e32 v146, 0x4b800000, v145
	v_cndmask_b32_e32 v145, v145, v146, vcc
	v_rsq_f32_e32 v144, v144
	v_rsq_f32_e32 v145, v145
	s_nop 0
	v_pk_mul_f32 v[146:147], v[144:145], s[0:1] op_sel_hi:[1,0]
	s_nop 0
	v_cndmask_b32_e64 v144, v144, v146, s[42:43]
	v_cndmask_b32_e32 v145, v145, v147, vcc
	v_mov_b32_e32 v146, v136
	v_mov_b32_e32 v147, v140
	v_mov_b32_e32 v140, v137
	v_pk_add_f32 v[136:137], v[146:147], v[140:141]
	v_mov_b32_e32 v140, v138
	v_mov_b32_e32 v141, v142
	v_mov_b32_e32 v142, v139
	v_pk_add_f32 v[138:139], v[140:141], v[142:143]
	s_nop 0
	v_pk_add_f32 v[136:137], v[136:137], v[138:139]
	ds_bpermute_b32 v138, v175, v136
	ds_bpermute_b32 v139, v175, v137
	s_waitcnt lgkmcnt(0)
	v_pk_add_f32 v[136:137], v[136:137], v[138:139]
	ds_bpermute_b32 v138, v173, v136
	ds_bpermute_b32 v139, v173, v137
	s_waitcnt lgkmcnt(0)
	v_pk_add_f32 v[136:137], v[136:137], v[138:139]
	s_nop 0
	v_pk_fma_f32 v[136:137], v[136:137], s[2:3], v[180:181] op_sel_hi:[1,0,0]
	s_nop 0
	v_mul_f32_e32 v138, 0x4b800000, v136
	v_cmp_gt_f32_e64 s[42:43], s19, v136
	v_cmp_gt_f32_e32 vcc, s19, v137
	s_nop 0
	v_cndmask_b32_e64 v136, v136, v138, s[42:43]
	v_mul_f32_e32 v138, 0x4b800000, v137
	v_cndmask_b32_e32 v137, v137, v138, vcc
	v_rsq_f32_e32 v136, v136
	v_rsq_f32_e32 v137, v137
	s_nop 0
	v_pk_mul_f32 v[138:139], v[136:137], s[0:1] op_sel_hi:[1,0]
	s_nop 0
	v_cndmask_b32_e64 v140, v136, v138, s[42:43]
	v_cndmask_b32_e32 v141, v137, v139, vcc
	v_mov_b32_e32 v136, v132
	v_mov_b32_e32 v137, v128
	v_mov_b32_e32 v128, v133
	v_mov_b32_e32 v132, v134
	v_mov_b32_e32 v133, v130
	v_mov_b32_e32 v130, v135
	v_pk_add_f32 v[128:129], v[136:137], v[128:129]
	v_pk_add_f32 v[130:131], v[132:133], v[130:131]
	s_nop 0
	v_pk_add_f32 v[128:129], v[128:129], v[130:131]
	ds_bpermute_b32 v130, v175, v128
	ds_bpermute_b32 v131, v175, v129
	s_waitcnt lgkmcnt(0)
	v_pk_add_f32 v[128:129], v[128:129], v[130:131]
	ds_bpermute_b32 v130, v173, v128
	ds_bpermute_b32 v131, v173, v129
	s_waitcnt lgkmcnt(0)
	v_pk_add_f32 v[128:129], v[128:129], v[130:131]
	s_nop 0
	v_pk_fma_f32 v[128:129], v[128:129], s[2:3], v[180:181] op_sel_hi:[1,0,0]
	s_nop 0
	v_mul_f32_e32 v130, 0x4b800000, v128
	v_cmp_gt_f32_e64 s[42:43], s19, v128
	v_cmp_gt_f32_e32 vcc, s19, v129
	s_nop 0
	v_cndmask_b32_e64 v128, v128, v130, s[42:43]
	v_mul_f32_e32 v130, 0x4b800000, v129
	v_cndmask_b32_e32 v129, v129, v130, vcc
	v_rsq_f32_e32 v128, v128
	v_rsq_f32_e32 v129, v129
	s_nop 0
	v_pk_mul_f32 v[130:131], v[128:129], s[0:1] op_sel_hi:[1,0]
	s_nop 0
	v_cndmask_b32_e64 v136, v128, v130, s[42:43]
	v_cndmask_b32_e32 v137, v129, v131, vcc
	s_branch .LBB0_397

	.amdhsa_kernel _Z8mega_fwd4Args
		.amdhsa_group_segment_fixed_size 0
		.amdhsa_private_segment_fixed_size 0
		.amdhsa_kernarg_size 400
		.amdhsa_user_sgpr_count 2
		.amdhsa_user_sgpr_dispatch_ptr 0
		.amdhsa_user_sgpr_queue_ptr 0
		.amdhsa_user_sgpr_kernarg_segment_ptr 1
		.amdhsa_user_sgpr_dispatch_id 0
		.amdhsa_user_sgpr_kernarg_preload_length 0
		.amdhsa_user_sgpr_kernarg_preload_offset 0
		.amdhsa_user_sgpr_private_segment_size 0
		.amdhsa_uses_dynamic_stack 0
		.amdhsa_enable_private_segment 0
		.amdhsa_system_sgpr_workgroup_id_x 1
		.amdhsa_system_sgpr_workgroup_id_y 0
		.amdhsa_system_sgpr_workgroup_id_z 0
		.amdhsa_system_sgpr_workgroup_info 0
		.amdhsa_system_vgpr_workitem_id 2
		.amdhsa_next_free_vgpr 252
		.amdhsa_next_free_sgpr 102
		.amdhsa_accum_offset 252
		.amdhsa_reserve_vcc 1
		.amdhsa_float_round_mode_32 0
		.amdhsa_float_round_mode_16_64 0
		.amdhsa_float_denorm_mode_32 3
		.amdhsa_float_denorm_mode_16_64 3
		.amdhsa_dx10_clamp 1
		.amdhsa_ieee_mode 1
		.amdhsa_fp16_overflow 0
		.amdhsa_tg_split 0
		.amdhsa_exception_fp_ieee_invalid_op 0
		.amdhsa_exception_fp_denorm_src 0
		.amdhsa_exception_fp_ieee_div_zero 0
		.amdhsa_exception_fp_ieee_overflow 0
		.amdhsa_exception_fp_ieee_underflow 0
		.amdhsa_exception_fp_ieee_inexact 0
		.amdhsa_exception_int_div_zero 0
	.end_amdhsa_kernel

amdhsa.kernels:
  - .agpr_count:     0
    .args:
      - .offset:         0
        .size:           144
        .value_kind:     by_value
      - .offset:         144
        .size:           4
        .value_kind:     hidden_block_count_x
      - .offset:         148
        .size:           4
        .value_kind:     hidden_block_count_y
      - .offset:         152
        .size:           4
        .value_kind:     hidden_block_count_z
      - .offset:         156
        .size:           2
        .value_kind:     hidden_group_size_x
      - .offset:         158
        .size:           2
        .value_kind:     hidden_group_size_y
      - .offset:         160
        .size:           2
        .value_kind:     hidden_group_size_z
      - .offset:         162
        .size:           2
        .value_kind:     hidden_remainder_x
      - .offset:         164
        .size:           2
        .value_kind:     hidden_remainder_y
      - .offset:         166
        .size:           2
        .value_kind:     hidden_remainder_z
      - .offset:         184
        .size:           8
        .value_kind:     hidden_global_offset_x
      - .offset:         192
        .size:           8
        .value_kind:     hidden_global_offset_y
      - .offset:         200
        .size:           8
        .value_kind:     hidden_global_offset_z
      - .offset:         208
        .size:           2
        .value_kind:     hidden_grid_dims
      - .offset:         232
        .size:           8
        .value_kind:     hidden_multigrid_sync_arg
      - .offset:         264
        .size:           4
        .value_kind:     hidden_dynamic_lds_size
    .group_segment_fixed_size: 0
    .kernarg_segment_align: 8
    .kernarg_segment_size: 400
    .language:       OpenCL C
    .language_version:
      - 2
      - 0
    .max_flat_workgroup_size: 512
    .name:           _Z8mega_fwd4Args
    .private_segment_fixed_size: 0
    .sgpr_count:     108
    .sgpr_spill_count: 222
    .symbol:         _Z8mega_fwd4Args.kd
    .uniform_work_group_size: 1
    .uses_dynamic_stack: false
    .vgpr_count:     252
    .vgpr_spill_count: 0
    .wavefront_size: 64
